# GEMM phase prologues: second tile's stages issued before (not after) the wait for the first tile's first pieces
# baseline (speedup 1.0000x reference)
; #define G_STAGE(bufoff, gbase, o0, h64) do { \
;         __builtin_amdgcn_global_load_lds((const unsigned*)((const char*)(gbase) + (o0)), (LAS unsigned*)(lds + (bufoff) + ldsw), 16, 0, 0); \
;         __builtin_amdgcn_global_load_lds((const unsigned*)((const char*)(gbase) + (h64) + (o0)), (LAS unsigned*)(lds + (bufoff) + ldsw + 8192), 16, 0, 0); } while (0)
; #define G_WAIT_V(n) asm volatile("s_waitcnt vmcnt(" #n ")" ::: "memory")
; #define G_BAR __builtin_amdgcn_s_barrier()
;     ...
;     const unsigned Rb0 = (unsigned)((R0 & ~31) + perm32(R0 & 31)), c1 = (unsigned)(C0 >> 4), c0b = (unsigned)((C0 & 15) * 2);
;     const unsigned ldsw = (unsigned)wid * 1024u;
;     const int aoff = lds_byte(wr * 64 + fr, fq * 8), boff = lds_byte(wc * 32 + fr, fq * 8);
;     constexpr Shape cs = shape_of<PH, SUB>(); constexpr bool FP8 = (PH == PH_MERGE && (SUB & 1) == 0);
;     const unsigned cA0 = (unsigned)R0 * cs.rsA + c1 * cs.ssA + c0b, cB0 = (Rb0 * cs.Kb + (unsigned)C0) * 2u;
;     ...
;     G_STAGE(G_SB(0, 0), cB, cB0, qB); G_STAGE(G_SA(0, 0), cA, cA0, qA); G_STAGE(G_SB(0, 1), cB + chB, cB0, qB); G_STAGE(G_SA(0, 1), cA + chA, cA0, qA);
;     if (wr == 1) G_BAR;
;     G_WAIT_V(4); G_BAR;
;     G_STAGE(G_SB(1, 0), cB + kB, cB0, qB); G_STAGE(G_SA(1, 0), cA + ckA, cA0, qA); G_STAGE(G_SB(1, 1), cB + chB + kB, cB0, qB);
;     G_WAIT_V(6); G_BAR;
.LBB0_205:
	v_lshl_add_u64 v[16:17], v[8:9], 0, s[46:47]
	s_add_i32 m0, s27, 0x18000
	s_mov_b64 s[4:5], 0x20080
	s_nop 0
	global_load_lds_dwordx4 v[16:17], off
	v_lshl_add_u64 v[16:17], v[8:9], 0, s[4:5]
	s_add_i32 m0, s27, 0x1a000
	s_add_i32 s31, s27, 0x8000
	global_load_lds_dwordx4 v[16:17], off
	v_lshl_add_u64 v[16:17], v[10:11], 0, s[46:47]
	s_mov_b32 m0, s31
	s_add_i32 s34, s27, 0xa000
	global_load_lds_dwordx4 v[16:17], off
	v_lshl_add_u64 v[10:11], v[10:11], 0, s[4:5]
	s_mov_b32 m0, s34
	s_mov_b64 s[4:5], 0x40080
	global_load_lds_dwordx4 v[10:11], off
	v_lshl_add_u64 v[10:11], v[8:9], 0, s[4:5]
	s_add_i32 m0, s27, 0x1c000
	s_mov_b64 s[4:5], 0x60080
	global_load_lds_dwordx4 v[10:11], off
	v_lshl_add_u64 v[8:9], v[8:9], 0, s[4:5]
	s_add_i32 m0, s27, 0x1e000
	v_lshlrev_b32_e32 v11, 2, v166
	global_load_lds_dwordx4 v[8:9], off
	s_waitcnt vmcnt(10)
	s_barrier
	v_and_b32_e32 v8, 15, v166
	v_and_b32_e32 v9, 48, v166
	v_lshlrev_b32_e32 v8, 6, v8
	v_or_b32_e32 v10, v8, v9
	s_lshl_b32 s4, s7, 13
	v_and_b32_e32 v11, 32, v11
	v_bitop3_b32 v8, v8, v11, v9 bitop3:0x36
	v_bitop3_b32 v9, v10, s4, v11 bitop3:0xde
	s_lshl_b32 s4, s6, 12
	s_and_b32 s4, s4, 0x3000
	s_add_u32 s35, s10, 0x6800000
	v_or_b32_e32 v167, s4, v8
	s_addc_u32 s36, s11, 0
	v_readlane_b32 s4, v231, 62
	s_bitcmp1_b32 s4, 0
	s_cselect_b32 s4, 0x2400000, 0
	s_add_u32 s37, s10, s4
	s_addc_u32 s38, s11, 0
	s_add_u32 s12, s10, 0xae00000
	v_lshlrev_b32_e32 v0, 14, v0
	s_waitcnt vmcnt(6)
	s_addc_u32 s13, s11, 0
	v_and_b32_e32 v0, 0xffff8000, v0
	s_add_u32 s10, s10, 0x1fe00000
	v_lshl_add_u32 v0, v12, 11, v0
	s_mov_b32 s6, 0
	s_addc_u32 s11, s11, 0
	v_add3_u32 v142, v0, v14, v13
	v_mov_b32_e32 v143, v1
	v_add_u32_e32 v172, 0, v9
	s_mov_b32 s39, 0
	s_barrier
	s_branch .LBB0_207

; #define G_STAGE(bufoff, gbase, o0, h64) do { \
;         __builtin_amdgcn_global_load_lds((const unsigned*)((const char*)(gbase) + (o0)), (LAS unsigned*)(lds + (bufoff) + ldsw), 16, 0, 0); \
;         __builtin_amdgcn_global_load_lds((const unsigned*)((const char*)(gbase) + (h64) + (o0)), (LAS unsigned*)(lds + (bufoff) + ldsw + 8192), 16, 0, 0); } while (0)
; #define G_WAIT_V(n) asm volatile("s_waitcnt vmcnt(" #n ")" ::: "memory")
; #define G_BAR __builtin_amdgcn_s_barrier()
;     ...
;     const unsigned Rb0 = (unsigned)((R0 & ~31) + perm32(R0 & 31)), c1 = (unsigned)(C0 >> 4), c0b = (unsigned)((C0 & 15) * 2);
;     const unsigned ldsw = (unsigned)wid * 1024u;
;     const int aoff = lds_byte(wr * 64 + fr, fq * 8), boff = lds_byte(wc * 32 + fr, fq * 8);
;     constexpr Shape cs = shape_of<PH, SUB>(); constexpr bool FP8 = (PH == PH_MERGE && (SUB & 1) == 0);
;     const unsigned cA0 = (unsigned)R0 * cs.rsA + c1 * cs.ssA + c0b, cB0 = (Rb0 * cs.Kb + (unsigned)C0) * 2u;
;     ...
;     G_STAGE(G_SB(0, 0), cB, cB0, qB); G_STAGE(G_SA(0, 0), cA, cA0, qA); G_STAGE(G_SB(0, 1), cB + chB, cB0, qB); G_STAGE(G_SA(0, 1), cA + chA, cA0, qA);
;     if (wr == 1) G_BAR;
;     G_WAIT_V(4); G_BAR;
;     G_STAGE(G_SB(1, 0), cB + kB, cB0, qB); G_STAGE(G_SA(1, 0), cA + ckA, cA0, qA); G_STAGE(G_SB(1, 1), cB + chB + kB, cB0, qB);
;     G_WAIT_V(6); G_BAR;
.LBB0_443:
	v_and_b32_e32 v15, 15, v144
	v_lshlrev_b32_e32 v18, 2, v144
	v_and_b32_e32 v16, 48, v144
	v_lshlrev_b32_e32 v15, 6, v15
	v_and_b32_e32 v18, 32, v18
	s_lshl_b32 s2, s2, 12
	v_or_b32_e32 v17, v15, v16
	s_lshl_b32 s3, s3, 13
	v_bitop3_b32 v15, v15, v18, v16 bitop3:0x36
	s_and_b32 s2, s2, 0x3000
	v_bitop3_b32 v18, v17, s3, v18 bitop3:0xde
	v_or_b32_e32 v145, s2, v15
	v_lshl_add_u64 v[16:17], v[8:9], 0, s[46:47]
	s_add_i32 m0, s27, 0x18000
	s_mov_b64 s[2:3], 0x10080
	s_nop 0
	global_load_lds_dwordx4 v[16:17], off
	v_lshl_add_u64 v[16:17], v[8:9], 0, s[2:3]
	s_add_i32 m0, s27, 0x1a000
	s_add_i32 s31, s27, 0x8000
	global_load_lds_dwordx4 v[16:17], off
	v_lshl_add_u64 v[16:17], v[10:11], 0, s[46:47]
	s_mov_b32 m0, s31
	s_add_i32 s33, s27, 0xa000
	global_load_lds_dwordx4 v[16:17], off
	v_lshl_add_u64 v[10:11], v[10:11], 0, s[2:3]
	s_mov_b32 m0, s33
	s_mov_b64 s[2:3], 0x20080
	global_load_lds_dwordx4 v[10:11], off
	v_lshl_add_u64 v[10:11], v[8:9], 0, s[2:3]
	s_add_i32 m0, s27, 0x1c000
	s_mov_b64 s[2:3], 0x30080
	global_load_lds_dwordx4 v[10:11], off
	v_lshl_add_u64 v[8:9], v[8:9], 0, s[2:3]
	s_add_i32 m0, s27, 0x1e000
	s_waitcnt lgkmcnt(0)
	s_add_u32 s34, s10, 0x1be00000
	global_load_lds_dwordx4 v[8:9], off
	s_waitcnt vmcnt(10)
	s_barrier
	s_addc_u32 s35, s11, 0
	s_add_u32 s36, s10, 0x15e00000
	v_lshlrev_b32_e32 v0, 13, v0
	s_waitcnt vmcnt(6)
	s_addc_u32 s37, s11, 0
	v_and_b32_e32 v0, 0xffffc000, v0
	s_add_u32 s2, s10, 0x1de00000
	v_lshl_add_u32 v0, v12, 10, v0
	s_addc_u32 s3, s11, 0
	v_add3_u32 v138, v0, v14, v13
	v_mov_b32_e32 v139, v1
	s_mov_b32 s38, 0
	v_add_u32_e32 v146, 0, v18
	s_barrier
	s_branch .LBB0_445

; #define G_STAGE(bufoff, gbase, o0, h64) do { \
;         __builtin_amdgcn_global_load_lds((const unsigned*)((const char*)(gbase) + (o0)), (LAS unsigned*)(lds + (bufoff) + ldsw), 16, 0, 0); \
;         __builtin_amdgcn_global_load_lds((const unsigned*)((const char*)(gbase) + (h64) + (o0)), (LAS unsigned*)(lds + (bufoff) + ldsw + 8192), 16, 0, 0); } while (0)
; #define G_WAIT_V(n) asm volatile("s_waitcnt vmcnt(" #n ")" ::: "memory")
; #define G_BAR __builtin_amdgcn_s_barrier()
;     ...
;     const unsigned Rb0 = (unsigned)((R0 & ~31) + perm32(R0 & 31)), c1 = (unsigned)(C0 >> 4), c0b = (unsigned)((C0 & 15) * 2);
;     const unsigned ldsw = (unsigned)wid * 1024u;
;     const int aoff = lds_byte(wr * 64 + fr, fq * 8), boff = lds_byte(wc * 32 + fr, fq * 8);
;     constexpr Shape cs = shape_of<PH, SUB>(); constexpr bool FP8 = (PH == PH_MERGE && (SUB & 1) == 0);
;     const unsigned cA0 = (unsigned)R0 * cs.rsA + c1 * cs.ssA + c0b, cB0 = (Rb0 * cs.Kb + (unsigned)C0) * 2u;
;     ...
;     G_STAGE(G_SB(0, 0), cB, cB0, qB); G_STAGE(G_SA(0, 0), cA, cA0, qA); G_STAGE(G_SB(0, 1), cB + chB, cB0, qB); G_STAGE(G_SA(0, 1), cA + chA, cA0, qA);
;     if (wr == 1) G_BAR;
;     G_WAIT_V(4); G_BAR;
;     G_STAGE(G_SB(1, 0), cB + kB, cB0, qB); G_STAGE(G_SA(1, 0), cA + ckA, cA0, qA); G_STAGE(G_SB(1, 1), cB + chB + kB, cB0, qB);
;     G_WAIT_V(6); G_BAR;
.LBB0_736:
	v_readlane_b32 s4, v231, 62
	s_lshl_b32 s74, s4, 9
	s_lshl_b64 s[4:5], s[74:75], 2
	v_and_b32_e32 v0, 15, v182
	s_add_u32 s6, s6, s4
	v_and_b32_e32 v12, 48, v182
	v_lshlrev_b32_e32 v0, 6, v0
	v_lshlrev_b32_e32 v14, 2, v182
	s_addc_u32 s7, s7, s5
	v_or_b32_e32 v13, v0, v12
	s_lshl_b32 s4, s13, 13
	v_and_b32_e32 v14, 32, v14
	v_bitop3_b32 v0, v0, v14, v12 bitop3:0x36
	v_bitop3_b32 v14, v13, s4, v14 bitop3:0xde
	s_lshl_b32 s4, s12, 12
	s_and_b32 s4, s4, 0x3000
	v_or_b32_e32 v183, s4, v0
	v_lshl_add_u64 v[12:13], v[8:9], 0, s[46:47]
	s_add_i32 m0, s43, 0x18000
	s_mov_b64 s[4:5], 0x8080
	s_nop 0
	global_load_lds_dwordx4 v[12:13], off
	v_lshl_add_u64 v[12:13], v[8:9], 0, s[4:5]
	s_add_i32 m0, s43, 0x1a000
	s_add_i32 s53, s43, 0x8000
	global_load_lds_dwordx4 v[12:13], off
	v_lshl_add_u64 v[12:13], v[10:11], 0, s[46:47]
	s_mov_b32 m0, s53
	s_mov_b64 s[4:5], 0x100080
	s_add_i32 s54, s43, 0xa000
	global_load_lds_dwordx4 v[12:13], off
	v_lshl_add_u64 v[10:11], v[10:11], 0, s[4:5]
	s_mov_b32 m0, s54
	s_mov_b64 s[4:5], 0x10080
	global_load_lds_dwordx4 v[10:11], off
	v_lshl_add_u64 v[10:11], v[8:9], 0, s[4:5]
	s_add_i32 m0, s43, 0x1c000
	v_lshl_add_u64 v[8:9], v[8:9], 0, s[68:69]
	global_load_lds_dwordx4 v[10:11], off
	s_add_i32 m0, s43, 0x1e000
	v_readlane_b32 s22, v232, 59
	global_load_lds_dwordx4 v[8:9], off
	s_waitcnt vmcnt(10)
	s_barrier
	s_waitcnt vmcnt(6)
	s_add_u32 s10, s10, 0x15e00000
	v_readlane_b32 s23, v232, 60
	s_addc_u32 s11, s11, 0
	s_mov_b32 s55, 0
	v_add_u32_e32 v184, 0, v14
	v_readlane_b32 s33, v232, 54
	v_readlane_b32 s23, v232, 51
	s_barrier

; #define G_STAGE(bufoff, gbase, o0, h64) do { \
;         __builtin_amdgcn_global_load_lds((const unsigned*)((const char*)(gbase) + (o0)), (LAS unsigned*)(lds + (bufoff) + ldsw), 16, 0, 0); \
;         __builtin_amdgcn_global_load_lds((const unsigned*)((const char*)(gbase) + (h64) + (o0)), (LAS unsigned*)(lds + (bufoff) + ldsw + 8192), 16, 0, 0); } while (0)
; #define G_WAIT_V(n) asm volatile("s_waitcnt vmcnt(" #n ")" ::: "memory")
; #define G_BAR __builtin_amdgcn_s_barrier()
;     ...
;     const unsigned Rb0 = (unsigned)((R0 & ~31) + perm32(R0 & 31)), c1 = (unsigned)(C0 >> 4), c0b = (unsigned)((C0 & 15) * 2);
;     const unsigned ldsw = (unsigned)wid * 1024u;
;     const int aoff = lds_byte(wr * 64 + fr, fq * 8), boff = lds_byte(wc * 32 + fr, fq * 8);
;     constexpr Shape cs = shape_of<PH, SUB>(); constexpr bool FP8 = (PH == PH_MERGE && (SUB & 1) == 0);
;     const unsigned cA0 = (unsigned)R0 * cs.rsA + c1 * cs.ssA + c0b, cB0 = (Rb0 * cs.Kb + (unsigned)C0) * 2u;
;     ...
;     G_STAGE(G_SB(0, 0), cB, cB0, qB); G_STAGE(G_SA(0, 0), cA, cA0, qA); G_STAGE(G_SB(0, 1), cB + chB, cB0, qB); G_STAGE(G_SA(0, 1), cA + chA, cA0, qA);
;     if (wr == 1) G_BAR;
;     G_WAIT_V(4); G_BAR;
;     G_STAGE(G_SB(1, 0), cB + kB, cB0, qB); G_STAGE(G_SA(1, 0), cA + ckA, cA0, qA); G_STAGE(G_SB(1, 1), cB + chB + kB, cB0, qB);
;     G_WAIT_V(6); G_BAR;
.LBB0_798:
	v_and_b32_e32 v15, 15, v195
	v_and_b32_e32 v16, 48, v195
	v_lshlrev_b32_e32 v15, 6, v15
	v_lshlrev_b32_e32 v18, 2, v195
	v_or_b32_e32 v17, v15, v16
	s_lshl_b32 s4, s11, 13
	v_and_b32_e32 v18, 32, v18
	v_bitop3_b32 v15, v15, v18, v16 bitop3:0x36
	v_bitop3_b32 v18, v17, s4, v18 bitop3:0xde
	s_lshl_b32 s4, s10, 12
	s_and_b32 s4, s4, 0x3000
	v_or_b32_e32 v196, s4, v15
	v_lshl_add_u64 v[16:17], v[8:9], 0, s[46:47]
	s_add_i32 m0, s24, 0x18000
	s_mov_b64 s[4:5], 0x10080
	s_nop 0
	global_load_lds_dwordx4 v[16:17], off
	v_lshl_add_u64 v[16:17], v[8:9], 0, s[4:5]
	s_add_i32 m0, s24, 0x1a000
	s_mov_b64 s[4:5], 0x400000
	s_add_i32 s29, s24, 0x8000
	global_load_lds_dwordx4 v[16:17], off
	v_lshl_add_u64 v[16:17], v[10:11], 0, s[4:5]
	s_mov_b32 m0, s29
	s_add_i32 s30, s24, 0xa000
	global_load_lds_dwordx4 v[16:17], off
	v_lshl_add_u64 v[10:11], v[10:11], 0, s[84:85]
	s_mov_b32 m0, s30
	s_mov_b64 s[4:5], 0x20080
	global_load_lds_dwordx4 v[10:11], off
	v_lshl_add_u64 v[10:11], v[8:9], 0, s[4:5]
	s_add_i32 m0, s24, 0x1c000
	s_mov_b64 s[4:5], 0x30080
	global_load_lds_dwordx4 v[10:11], off
	v_lshl_add_u64 v[8:9], v[8:9], 0, s[4:5]
	s_add_i32 m0, s24, 0x1e000
	v_lshlrev_b32_e32 v0, 5, v0
	global_load_lds_dwordx4 v[8:9], off
	s_waitcnt vmcnt(10)
	s_barrier
	v_lshlrev_b32_e32 v8, 8, v12
	s_waitcnt vmcnt(6)
	v_and_b32_e32 v8, 0xfffffe00, v8
	v_add_u32_e32 v8, v13, v8
	v_readlane_b32 s4, v231, 11
	v_add3_u32 v166, v8, v0, v14
	v_mov_b32_e32 v167, v1
	s_mov_b32 s31, 0
	v_add_u32_e32 v197, 0, v18
	v_readlane_b32 s33, v231, 48
	s_mov_b32 s35, s4
	s_barrier
	v_readlane_b32 s5, v231, 12

; #define G_STAGE(bufoff, gbase, o0, h64) do { \
;         __builtin_amdgcn_global_load_lds((const unsigned*)((const char*)(gbase) + (o0)), (LAS unsigned*)(lds + (bufoff) + ldsw), 16, 0, 0); \
;         __builtin_amdgcn_global_load_lds((const unsigned*)((const char*)(gbase) + (h64) + (o0)), (LAS unsigned*)(lds + (bufoff) + ldsw + 8192), 16, 0, 0); } while (0)
; #define G_WAIT_V(n) asm volatile("s_waitcnt vmcnt(" #n ")" ::: "memory")
; #define G_BAR __builtin_amdgcn_s_barrier()
;     ...
;     const unsigned Rb0 = (unsigned)((R0 & ~31) + perm32(R0 & 31)), c1 = (unsigned)(C0 >> 4), c0b = (unsigned)((C0 & 15) * 2);
;     const unsigned ldsw = (unsigned)wid * 1024u;
;     const int aoff = lds_byte(wr * 64 + fr, fq * 8), boff = lds_byte(wc * 32 + fr, fq * 8);
;     constexpr Shape cs = shape_of<PH, SUB>(); constexpr bool FP8 = (PH == PH_MERGE && (SUB & 1) == 0);
;     const unsigned cA0 = (unsigned)R0 * cs.rsA + c1 * cs.ssA + c0b, cB0 = (Rb0 * cs.Kb + (unsigned)C0) * 2u;
;     ...
;     G_STAGE(G_SB(0, 0), cB, cB0, qB); G_STAGE(G_SA(0, 0), cA, cA0, qA); G_STAGE(G_SB(0, 1), cB + chB, cB0, qB); G_STAGE(G_SA(0, 1), cA + chA, cA0, qA);
;     if (wr == 1) G_BAR;
;     G_WAIT_V(4); G_BAR;
;     G_STAGE(G_SB(1, 0), cB + kB, cB0, qB); G_STAGE(G_SA(1, 0), cA + ckA, cA0, qA); G_STAGE(G_SB(1, 1), cB + chB + kB, cB0, qB);
;     G_WAIT_V(6); G_BAR;
.LBB0_866:
	v_and_b32_e32 v16, 15, v158
	v_and_b32_e32 v17, 48, v158
	v_lshlrev_b32_e32 v16, 6, v16
	v_lshlrev_b32_e32 v19, 2, v158
	v_or_b32_e32 v18, v16, v17
	s_lshl_b32 s4, s7, 13
	v_and_b32_e32 v19, 32, v19
	v_bitop3_b32 v18, v18, s4, v19 bitop3:0xde
	s_lshl_b32 s4, s6, 12
	v_bitop3_b32 v16, v16, v19, v17 bitop3:0x36
	s_and_b32 s4, s4, 0x3000
	v_or_b32_e32 v159, s4, v16
	v_lshl_add_u64 v[16:17], v[10:11], 0, s[46:47]
	s_add_i32 m0, s22, 0x18000
	s_mov_b64 s[4:5], 0x10080
	s_nop 0
	global_load_lds_dwordx4 v[16:17], off
	v_lshl_add_u64 v[16:17], v[10:11], 0, s[4:5]
	s_add_i32 m0, s22, 0x1a000
	s_add_i32 s26, s22, 0x8000
	global_load_lds_dwordx4 v[16:17], off
	v_lshl_add_u64 v[16:17], v[12:13], 0, s[46:47]
	s_mov_b32 m0, s26
	s_add_i32 s27, s22, 0xa000
	global_load_lds_dwordx4 v[16:17], off
	v_lshl_add_u64 v[12:13], v[12:13], 0, s[66:67]
	s_mov_b32 m0, s27
	s_mov_b64 s[4:5], 0x20080
	global_load_lds_dwordx4 v[12:13], off
	v_lshl_add_u64 v[12:13], v[10:11], 0, s[4:5]
	s_add_i32 m0, s22, 0x1c000
	s_mov_b64 s[4:5], 0x30080
	global_load_lds_dwordx4 v[12:13], off
	v_lshl_add_u64 v[10:11], v[10:11], 0, s[4:5]
	s_add_i32 m0, s22, 0x1e000
	s_mov_b32 s4, 0x16000
	global_load_lds_dwordx4 v[10:11], off
	s_waitcnt vmcnt(10)
	s_barrier
	s_waitcnt vmcnt(6)
	v_lshrrev_b32_e32 v11, 1, v14
	v_mul_lo_u32 v10, v9, s76
	s_add_u32 s29, s8, 0x2000000
	v_mad_u64_u32 v[10:11], s[4:5], v11, s4, v[10:11]
	s_addc_u32 s30, s9, 0
	v_add3_u32 v152, v10, v8, v15
	v_mov_b32_e32 v153, v1
	s_mov_b32 s33, 0
	v_add_u32_e32 v236, 0, v18
	s_mov_b32 s36, 0
	s_mov_b32 s31, 0
	s_barrier

; #define G_STAGE(bufoff, gbase, o0, h64) do { \
;         __builtin_amdgcn_global_load_lds((const unsigned*)((const char*)(gbase) + (o0)), (LAS unsigned*)(lds + (bufoff) + ldsw), 16, 0, 0); \
;         __builtin_amdgcn_global_load_lds((const unsigned*)((const char*)(gbase) + (h64) + (o0)), (LAS unsigned*)(lds + (bufoff) + ldsw + 8192), 16, 0, 0); } while (0)
; #define G_WAIT_V(n) asm volatile("s_waitcnt vmcnt(" #n ")" ::: "memory")
; #define G_BAR __builtin_amdgcn_s_barrier()
;     ...
;     f32x4 acc[2][2][4][2];
; #pragma unroll
;     for (int a = 0; a < 2; ++a)
; #pragma unroll
;         for (int b = 0; b < 2; ++b)
; #pragma unroll
;             for (int m = 0; m < 4; ++m)
; #pragma unroll
;                 for (int n = 0; n < 2; ++n) acc[a][b][m][n] = (f32x4){0.f, 0.f, 0.f, 0.f};
;     ...
;     G_STAGE(G_SB(0, 0), cB, cB0, qB); G_STAGE(G_SA(0, 0), cA, cA0, qA); G_STAGE(G_SB(0, 1), cB + chB, cB0, qB); G_STAGE(G_SA(0, 1), cA + chA, cA0, qA);
;     if (wr == 1) G_BAR;
;     G_WAIT_V(4); G_BAR;
;     G_STAGE(G_SB(1, 0), cB + kB, cB0, qB); G_STAGE(G_SA(1, 0), cA + ckA, cA0, qA); G_STAGE(G_SB(1, 1), cB + chB + kB, cB0, qB);
;     G_WAIT_V(6); G_BAR;
.LBB0_882:
	v_lshl_add_u64 v[14:15], v[2:3], 0, s[46:47]
	s_add_i32 m0, s22, 0x18000
	s_mov_b64 s[4:5], 0x10080
	s_nop 0
	global_load_lds_dwordx4 v[14:15], off
	v_lshl_add_u64 v[14:15], v[2:3], 0, s[4:5]
	s_add_i32 m0, s22, 0x1a000
	s_add_i32 s26, s22, 0x8000
	global_load_lds_dwordx4 v[14:15], off
	v_lshl_add_u64 v[14:15], v[8:9], 0, s[46:47]
	s_mov_b32 m0, s26
	s_add_i32 s27, s22, 0xa000
	global_load_lds_dwordx4 v[14:15], off
	v_lshl_add_u64 v[8:9], v[8:9], 0, s[66:67]
	s_mov_b32 m0, s27
	s_mov_b64 s[4:5], 0x20080
	global_load_lds_dwordx4 v[8:9], off
	v_lshl_add_u64 v[8:9], v[2:3], 0, s[4:5]
	s_add_i32 m0, s22, 0x1c000
	s_mov_b64 s[4:5], 0x30080
	global_load_lds_dwordx4 v[8:9], off
	v_lshl_add_u64 v[2:3], v[2:3], 0, s[4:5]
	s_add_i32 m0, s22, 0x1e000
	v_lshlrev_b32_e32 v9, 2, v174
	global_load_lds_dwordx4 v[2:3], off
	s_waitcnt vmcnt(10)
	s_barrier
	v_and_b32_e32 v2, 15, v174
	s_lshl_b32 s2, s2, 12
	v_and_b32_e32 v3, 48, v174
	v_lshlrev_b32_e32 v2, 6, v2
	s_lshl_b32 s3, s3, 13
	v_and_b32_e32 v9, 32, v9
	s_and_b32 s2, s2, 0x3000
	v_or_b32_e32 v8, v2, v3
	v_bitop3_b32 v2, v2, v9, v3 bitop3:0x36
	s_waitcnt lgkmcnt(0)
	s_add_u32 s29, s10, 0xae00000
	v_or_b32_e32 v175, s2, v2
	s_addc_u32 s30, s11, 0
	v_readlane_b32 s2, v231, 62
	s_bitcmp1_b32 s2, 0
	s_cselect_b32 s2, 0x2400000, 0
	s_add_u32 s2, s10, s2
	s_addc_u32 s4, s11, 0
	s_add_u32 s31, s2, 0xc00000
	s_addc_u32 s34, s4, 0
	v_lshrrev_b32_e32 v3, 1, v10
	v_mul_lo_u32 v2, v11, s76
	s_mov_b32 s2, 0x16000
	s_add_u32 s10, s10, 0x17e00000
	v_mad_u64_u32 v[2:3], s[4:5], v3, s2, v[2:3]
	v_bitop3_b32 v8, v8, s3, v9 bitop3:0xde
	s_waitcnt vmcnt(6)
	s_addc_u32 s11, s11, 0
	v_add3_u32 v156, v2, v0, v12
	v_mov_b32_e32 v2, v1
	v_mov_b32_e32 v3, v1
	s_add_u32 s35, s8, 0x2000000
	v_mov_b32_e32 v0, v1
	v_add_u32_e32 v176, 0, v8
	v_mov_b64_e32 v[10:11], v[2:3]
	v_mov_b64_e32 v[14:15], v[2:3]
	v_mov_b64_e32 v[18:19], v[2:3]
	v_mov_b64_e32 v[22:23], v[2:3]
	v_mov_b64_e32 v[26:27], v[2:3]
	v_mov_b64_e32 v[30:31], v[2:3]
	v_mov_b64_e32 v[34:35], v[2:3]
	v_mov_b64_e32 v[38:39], v[2:3]
	v_mov_b64_e32 v[42:43], v[2:3]
	v_mov_b64_e32 v[46:47], v[2:3]
	v_mov_b64_e32 v[50:51], v[2:3]
	v_mov_b64_e32 v[54:55], v[2:3]
	v_mov_b64_e32 v[58:59], v[2:3]
	v_mov_b64_e32 v[62:63], v[2:3]
	v_mov_b64_e32 v[66:67], v[2:3]
	v_mov_b64_e32 v[70:71], v[2:3]
	v_mov_b64_e32 v[74:75], v[2:3]
	v_mov_b64_e32 v[78:79], v[2:3]
	v_mov_b64_e32 v[82:83], v[2:3]
	v_mov_b64_e32 v[86:87], v[2:3]
	v_mov_b64_e32 v[90:91], v[2:3]
	v_mov_b64_e32 v[94:95], v[2:3]
	v_mov_b64_e32 v[98:99], v[2:3]
	v_mov_b64_e32 v[102:103], v[2:3]
	v_mov_b64_e32 v[114:115], v[2:3]
	v_mov_b64_e32 v[118:119], v[2:3]
	v_mov_b64_e32 v[122:123], v[2:3]
	v_mov_b64_e32 v[126:127], v[2:3]
	v_mov_b64_e32 v[130:131], v[2:3]
	v_mov_b64_e32 v[134:135], v[2:3]
	v_mov_b64_e32 v[110:111], v[2:3]
	v_mov_b64_e32 v[106:107], v[2:3]
	s_mov_b32 s3, 0
	s_addc_u32 s36, s9, 0
	v_mov_b32_e32 v157, v1
	v_mov_b64_e32 v[8:9], v[0:1]
	v_mov_b64_e32 v[12:13], v[0:1]
	v_mov_b64_e32 v[16:17], v[0:1]
	v_mov_b64_e32 v[20:21], v[0:1]
	v_mov_b64_e32 v[24:25], v[0:1]
	v_mov_b64_e32 v[28:29], v[0:1]
	v_mov_b64_e32 v[32:33], v[0:1]
	v_mov_b64_e32 v[36:37], v[0:1]
	v_mov_b64_e32 v[40:41], v[0:1]
	v_mov_b64_e32 v[44:45], v[0:1]
	v_mov_b64_e32 v[48:49], v[0:1]
	v_mov_b64_e32 v[52:53], v[0:1]
	v_mov_b64_e32 v[56:57], v[0:1]
	v_mov_b64_e32 v[60:61], v[0:1]
	v_mov_b64_e32 v[64:65], v[0:1]
	v_mov_b64_e32 v[68:69], v[0:1]
	v_mov_b64_e32 v[72:73], v[0:1]
	v_mov_b64_e32 v[76:77], v[0:1]
	v_mov_b64_e32 v[80:81], v[0:1]
	v_mov_b64_e32 v[84:85], v[0:1]
	v_mov_b64_e32 v[88:89], v[0:1]
	v_mov_b64_e32 v[92:93], v[0:1]
	v_mov_b64_e32 v[96:97], v[0:1]
	v_mov_b64_e32 v[100:101], v[0:1]
	v_mov_b64_e32 v[112:113], v[0:1]
	v_mov_b64_e32 v[116:117], v[0:1]
	v_mov_b64_e32 v[120:121], v[0:1]
	v_mov_b64_e32 v[124:125], v[0:1]
	v_mov_b64_e32 v[128:129], v[0:1]
	v_mov_b64_e32 v[132:133], v[0:1]
	v_mov_b64_e32 v[108:109], v[0:1]
	v_mov_b64_e32 v[104:105], v[0:1]
	s_mov_b32 s2, 0
	s_mov_b32 s37, 0
	s_barrier
	s_branch .LBB0_885

; #define G_STAGE(bufoff, gbase, o0, h64) do { \
;         __builtin_amdgcn_global_load_lds((const unsigned*)((const char*)(gbase) + (o0)), (LAS unsigned*)(lds + (bufoff) + ldsw), 16, 0, 0); \
;         __builtin_amdgcn_global_load_lds((const unsigned*)((const char*)(gbase) + (h64) + (o0)), (LAS unsigned*)(lds + (bufoff) + ldsw + 8192), 16, 0, 0); } while (0)
; #define G_WAIT_V(n) asm volatile("s_waitcnt vmcnt(" #n ")" ::: "memory")
; #define G_BAR __builtin_amdgcn_s_barrier()
;     ...
;     const unsigned Rb0 = (unsigned)((R0 & ~31) + perm32(R0 & 31)), c1 = (unsigned)(C0 >> 4), c0b = (unsigned)((C0 & 15) * 2);
;     const unsigned ldsw = (unsigned)wid * 1024u;
;     const int aoff = lds_byte(wr * 64 + fr, fq * 8), boff = lds_byte(wc * 32 + fr, fq * 8);
;     constexpr Shape cs = shape_of<PH, SUB>(); constexpr bool FP8 = (PH == PH_MERGE && (SUB & 1) == 0);
;     const unsigned cA0 = (unsigned)R0 * cs.rsA + c1 * cs.ssA + c0b, cB0 = (Rb0 * cs.Kb + (unsigned)C0) * 2u;
;     ...
;     G_STAGE(G_SB(0, 0), cB, cB0, qB); G_STAGE(G_SA(0, 0), cA, cA0, qA); G_STAGE(G_SB(0, 1), cB + chB, cB0, qB); G_STAGE(G_SA(0, 1), cA + chA, cA0, qA);
;     if (wr == 1) G_BAR;
;     G_WAIT_V(4); G_BAR;
;     G_STAGE(G_SB(1, 0), cB + kB, cB0, qB); G_STAGE(G_SA(1, 0), cA + ckA, cA0, qA); G_STAGE(G_SB(1, 1), cB + chB + kB, cB0, qB);
;     G_WAIT_V(6); G_BAR;
.LBB0_1030:
	v_and_b32_e32 v15, 15, v180
	v_and_b32_e32 v16, 48, v180
	v_lshlrev_b32_e32 v15, 6, v15
	v_lshlrev_b32_e32 v18, 2, v180
	v_or_b32_e32 v17, v15, v16
	s_lshl_b32 s4, s11, 13
	v_and_b32_e32 v18, 32, v18
	v_bitop3_b32 v15, v15, v18, v16 bitop3:0x36
	v_bitop3_b32 v18, v17, s4, v18 bitop3:0xde
	s_lshl_b32 s4, s10, 12
	s_and_b32 s4, s4, 0x3000
	v_or_b32_e32 v181, s4, v15
	v_lshl_add_u64 v[16:17], v[8:9], 0, s[46:47]
	s_add_i32 m0, s24, 0x18000
	s_mov_b64 s[4:5], 0x20080
	s_nop 0
	global_load_lds_dwordx4 v[16:17], off
	v_lshl_add_u64 v[16:17], v[8:9], 0, s[4:5]
	s_add_i32 m0, s24, 0x1a000
	s_add_i32 s29, s24, 0x8000
	global_load_lds_dwordx4 v[16:17], off
	v_lshl_add_u64 v[16:17], v[10:11], 0, s[46:47]
	s_mov_b32 m0, s29
	s_add_i32 s30, s24, 0xa000
	global_load_lds_dwordx4 v[16:17], off
	v_lshl_add_u64 v[10:11], v[10:11], 0, s[4:5]
	s_mov_b32 m0, s30
	s_mov_b64 s[4:5], 0x40080
	global_load_lds_dwordx4 v[10:11], off
	v_lshl_add_u64 v[10:11], v[8:9], 0, s[4:5]
	s_add_i32 m0, s24, 0x1c000
	s_mov_b64 s[4:5], 0x60080
	global_load_lds_dwordx4 v[10:11], off
	v_lshl_add_u64 v[8:9], v[8:9], 0, s[4:5]
	s_add_i32 m0, s24, 0x1e000
	s_waitcnt lgkmcnt(0)
	s_add_u32 s31, s12, 0x17e00000
	global_load_lds_dwordx4 v[8:9], off
	s_waitcnt vmcnt(10)
	s_barrier
	s_addc_u32 s34, s13, 0
	v_readlane_b32 s4, v231, 62
	s_bitcmp1_b32 s4, 0
	s_cselect_b32 s4, 0x2400000, 0
	s_add_u32 s4, s12, s4
	s_addc_u32 s5, s13, 0
	s_add_u32 s36, s4, 0xf00000
	s_addc_u32 s37, s5, 0
	s_add_u32 s10, s12, 0x6800000
	v_lshlrev_b32_e32 v0, 14, v0
	s_waitcnt vmcnt(6)
	s_addc_u32 s11, s13, 0
	v_and_b32_e32 v0, 0xffff8000, v0
	s_add_u32 s38, s12, 0xaa00000
	v_lshl_add_u32 v0, v12, 11, v0
	s_mov_b32 s35, 0
	s_addc_u32 s39, s13, 0
	v_add3_u32 v166, v0, v14, v13
	v_mov_b32_e32 v167, v1
	v_add_u32_e32 v182, 0, v18
	s_barrier
	s_branch .LBB0_1032

; #define G_STAGE(bufoff, gbase, o0, h64) do { \
;         __builtin_amdgcn_global_load_lds((const unsigned*)((const char*)(gbase) + (o0)), (LAS unsigned*)(lds + (bufoff) + ldsw), 16, 0, 0); \
;         __builtin_amdgcn_global_load_lds((const unsigned*)((const char*)(gbase) + (h64) + (o0)), (LAS unsigned*)(lds + (bufoff) + ldsw + 8192), 16, 0, 0); } while (0)
; #define G_WAIT_V(n) asm volatile("s_waitcnt vmcnt(" #n ")" ::: "memory")
; #define G_BAR __builtin_amdgcn_s_barrier()
;     ...
;     const unsigned Rb0 = (unsigned)((R0 & ~31) + perm32(R0 & 31)), c1 = (unsigned)(C0 >> 4), c0b = (unsigned)((C0 & 15) * 2);
;     const unsigned ldsw = (unsigned)wid * 1024u;
;     const int aoff = lds_byte(wr * 64 + fr, fq * 8), boff = lds_byte(wc * 32 + fr, fq * 8);
;     constexpr Shape cs = shape_of<PH, SUB>(); constexpr bool FP8 = (PH == PH_MERGE && (SUB & 1) == 0);
;     const unsigned cA0 = (unsigned)R0 * cs.rsA + c1 * cs.ssA + c0b, cB0 = (Rb0 * cs.Kb + (unsigned)C0) * 2u;
;     ...
;     G_STAGE(G_SB(0, 0), cB, cB0, qB); G_STAGE(G_SA(0, 0), cA, cA0, qA); G_STAGE(G_SB(0, 1), cB + chB, cB0, qB); G_STAGE(G_SA(0, 1), cA + chA, cA0, qA);
;     if (wr == 1) G_BAR;
;     G_WAIT_V(4); G_BAR;
;     G_STAGE(G_SB(1, 0), cB + kB, cB0, qB); G_STAGE(G_SA(1, 0), cA + ckA, cA0, qA); G_STAGE(G_SB(1, 1), cB + chB + kB, cB0, qB);
;     G_WAIT_V(6); G_BAR;
.LBB0_1114:
	v_and_b32_e32 v15, 15, v148
	v_and_b32_e32 v16, 48, v148
	v_lshlrev_b32_e32 v15, 6, v15
	v_lshlrev_b32_e32 v18, 2, v148
	v_or_b32_e32 v17, v15, v16
	s_lshl_b32 s4, s7, 13
	v_and_b32_e32 v18, 32, v18
	v_bitop3_b32 v15, v15, v18, v16 bitop3:0x36
	v_bitop3_b32 v18, v17, s4, v18 bitop3:0xde
	s_lshl_b32 s4, s6, 12
	s_and_b32 s4, s4, 0x3000
	v_or_b32_e32 v149, s4, v15
	v_lshl_add_u64 v[16:17], v[8:9], 0, s[46:47]
	s_add_i32 m0, s26, 0x18000
	s_mov_b64 s[4:5], 0x20080
	s_nop 0
	global_load_lds_dwordx4 v[16:17], off
	v_lshl_add_u64 v[16:17], v[8:9], 0, s[4:5]
	s_add_i32 m0, s26, 0x1a000
	s_add_i32 s31, s26, 0x8000
	global_load_lds_dwordx4 v[16:17], off
	v_lshl_add_u64 v[16:17], v[10:11], 0, s[46:47]
	s_mov_b32 m0, s31
	s_add_i32 s34, s26, 0xa000
	global_load_lds_dwordx4 v[16:17], off
	v_lshl_add_u64 v[10:11], v[10:11], 0, s[4:5]
	s_mov_b32 m0, s34
	s_mov_b64 s[4:5], 0x40080
	global_load_lds_dwordx4 v[10:11], off
	v_lshl_add_u64 v[10:11], v[8:9], 0, s[4:5]
	s_add_i32 m0, s26, 0x1c000
	s_mov_b64 s[4:5], 0x60080
	global_load_lds_dwordx4 v[10:11], off
	v_lshl_add_u64 v[8:9], v[8:9], 0, s[4:5]
	s_add_i32 m0, s26, 0x1e000
	s_add_u32 s6, s2, 0xae00000
	global_load_lds_dwordx4 v[8:9], off
	s_waitcnt vmcnt(10)
	s_barrier
	v_lshlrev_b32_e32 v8, 14, v12
	s_waitcnt vmcnt(6)
	v_and_b32_e32 v8, 0xffff8000, v8
	s_addc_u32 s7, s3, 0
	v_lshl_add_u32 v0, v0, 11, v8
	v_readlane_b32 s2, v231, 24
	v_add3_u32 v138, v0, v13, v14
	v_mov_b32_e32 v139, v1
	s_mov_b32 s38, 0
	v_add_u32_e32 v150, 0, v18
	v_readlane_b32 s33, v231, 49
	s_mov_b32 s37, s2
	s_mov_b32 s35, 0
	s_barrier
	v_readlane_b32 s3, v231, 25

; #define G_STAGE(bufoff, gbase, o0, h64) do { \
;         __builtin_amdgcn_global_load_lds((const unsigned*)((const char*)(gbase) + (o0)), (LAS unsigned*)(lds + (bufoff) + ldsw), 16, 0, 0); \
;         __builtin_amdgcn_global_load_lds((const unsigned*)((const char*)(gbase) + (h64) + (o0)), (LAS unsigned*)(lds + (bufoff) + ldsw + 8192), 16, 0, 0); } while (0)
; #define G_WAIT_V(n) asm volatile("s_waitcnt vmcnt(" #n ")" ::: "memory")
; #define G_BAR __builtin_amdgcn_s_barrier()
;     ...
;     const unsigned Rb0 = (unsigned)((R0 & ~31) + perm32(R0 & 31)), c1 = (unsigned)(C0 >> 4), c0b = (unsigned)((C0 & 15) * 2);
;     const unsigned ldsw = (unsigned)wid * 1024u;
;     const int aoff = lds_byte(wr * 64 + fr, fq * 8), boff = lds_byte(wc * 32 + fr, fq * 8);
;     constexpr Shape cs = shape_of<PH, SUB>(); constexpr bool FP8 = (PH == PH_MERGE && (SUB & 1) == 0);
;     const unsigned cA0 = (unsigned)R0 * cs.rsA + c1 * cs.ssA + c0b, cB0 = (Rb0 * cs.Kb + (unsigned)C0) * 2u;
;     ...
;     G_STAGE(G_SB(0, 0), cB, cB0, qB); G_STAGE(G_SA(0, 0), cA, cA0, qA); G_STAGE(G_SB(0, 1), cB + chB, cB0, qB); G_STAGE(G_SA(0, 1), cA + chA, cA0, qA);
;     if (wr == 1) G_BAR;
;     G_WAIT_V(4); G_BAR;
;     G_STAGE(G_SB(1, 0), cB + kB, cB0, qB); G_STAGE(G_SA(1, 0), cA + ckA, cA0, qA); G_STAGE(G_SB(1, 1), cB + chB + kB, cB0, qB);
;     G_WAIT_V(6); G_BAR;
.LBB0_1178:
	v_and_b32_e32 v15, 15, v184
	v_and_b32_e32 v16, 48, v184
	v_lshlrev_b32_e32 v15, 6, v15
	v_lshlrev_b32_e32 v18, 2, v184
	v_or_b32_e32 v17, v15, v16
	s_lshl_b32 s4, s13, 13
	v_and_b32_e32 v18, 32, v18
	v_bitop3_b32 v15, v15, v18, v16 bitop3:0x36
	v_bitop3_b32 v18, v17, s4, v18 bitop3:0xde
	v_lshl_add_u64 v[16:17], v[8:9], 0, s[46:47]
	s_add_i32 m0, s26, 0x18000
	s_lshl_b32 s4, s12, 12
	s_nop 0
	global_load_lds_dwordx4 v[16:17], off
	v_lshl_add_u64 v[16:17], v[8:9], 0, s[66:67]
	s_add_i32 m0, s26, 0x1a000
	s_add_i32 s31, s26, 0x8000
	s_and_b32 s4, s4, 0x3000
	global_load_lds_dwordx4 v[16:17], off
	v_lshl_add_u64 v[16:17], v[10:11], 0, s[46:47]
	s_mov_b32 m0, s31
	s_add_i32 s34, s26, 0xa000
	v_or_b32_e32 v185, s4, v15
	global_load_lds_dwordx4 v[16:17], off
	v_lshl_add_u64 v[10:11], v[10:11], 0, s[66:67]
	s_mov_b32 m0, s34
	s_mov_b64 s[4:5], 0xb0080
	global_load_lds_dwordx4 v[10:11], off
	v_lshl_add_u64 v[10:11], v[8:9], 0, s[4:5]
	s_add_i32 m0, s26, 0x1c000
	s_mov_b64 s[4:5], 0x108080
	global_load_lds_dwordx4 v[10:11], off
	v_lshl_add_u64 v[8:9], v[8:9], 0, s[4:5]
	s_add_i32 m0, s26, 0x1e000
	s_waitcnt lgkmcnt(0)
	s_add_u32 s35, s8, 0xae00000
	global_load_lds_dwordx4 v[8:9], off
	s_waitcnt vmcnt(10)
	s_barrier
	s_addc_u32 s36, s9, 0
	v_readlane_b32 s4, v231, 62
	s_bitcmp1_b32 s4, 0
	s_cselect_b32 s4, 0x2400000, 0
	s_add_u32 s4, s8, s4
	s_addc_u32 s5, s9, 0
	s_add_u32 s38, s4, 0x1c00000
	s_addc_u32 s39, s5, 0
	s_add_u32 s12, s8, 0x6800000
	s_waitcnt vmcnt(6)
	s_addc_u32 s13, s9, 0
	v_lshrrev_b32_e32 v9, 1, v12
	v_mul_lo_u32 v8, v13, s76
	s_mov_b32 s4, 0x16000
	s_add_u32 s40, s8, 0x17e00000
	v_mad_u64_u32 v[8:9], s[4:5], v9, s4, v[8:9]
	s_mov_b32 s37, 0
	s_addc_u32 s41, s9, 0
	v_add3_u32 v174, v8, v0, v14
	v_mov_b32_e32 v175, v1
	v_add_u32_e32 v195, 0, v18
	s_barrier
	s_branch .LBB0_1180

; #define G_STAGE(bufoff, gbase, o0, h64) do { \
;         __builtin_amdgcn_global_load_lds((const unsigned*)((const char*)(gbase) + (o0)), (LAS unsigned*)(lds + (bufoff) + ldsw), 16, 0, 0); \
;         __builtin_amdgcn_global_load_lds((const unsigned*)((const char*)(gbase) + (h64) + (o0)), (LAS unsigned*)(lds + (bufoff) + ldsw + 8192), 16, 0, 0); } while (0)
; #define G_WAIT_V(n) asm volatile("s_waitcnt vmcnt(" #n ")" ::: "memory")
; #define G_BAR __builtin_amdgcn_s_barrier()
;     ...
;     const unsigned Rb0 = (unsigned)((R0 & ~31) + perm32(R0 & 31)), c1 = (unsigned)(C0 >> 4), c0b = (unsigned)((C0 & 15) * 2);
;     const unsigned ldsw = (unsigned)wid * 1024u;
;     const int aoff = lds_byte(wr * 64 + fr, fq * 8), boff = lds_byte(wc * 32 + fr, fq * 8);
;     constexpr Shape cs = shape_of<PH, SUB>(); constexpr bool FP8 = (PH == PH_MERGE && (SUB & 1) == 0);
;     const unsigned cA0 = (unsigned)R0 * cs.rsA + c1 * cs.ssA + c0b, cB0 = (Rb0 * cs.Kb + (unsigned)C0) * 2u;
;     ...
;     G_STAGE(G_SB(0, 0), cB, cB0, qB); G_STAGE(G_SA(0, 0), cA, cA0, qA); G_STAGE(G_SB(0, 1), cB + chB, cB0, qB); G_STAGE(G_SA(0, 1), cA + chA, cA0, qA);
;     if (wr == 1) G_BAR;
;     G_WAIT_V(4); G_BAR;
;     G_STAGE(G_SB(1, 0), cB + kB, cB0, qB); G_STAGE(G_SA(1, 0), cA + ckA, cA0, qA); G_STAGE(G_SB(1, 1), cB + chB + kB, cB0, qB);
;     G_WAIT_V(6); G_BAR;
.LBB0_1256:
	v_and_b32_e32 v12, 15, v136
	v_and_b32_e32 v13, 48, v136
	v_lshlrev_b32_e32 v12, 6, v12
	v_lshlrev_b32_e32 v15, 2, v136
	v_or_b32_e32 v14, v12, v13
	s_lshl_b32 s4, s7, 13
	v_and_b32_e32 v15, 32, v15
	v_bitop3_b32 v14, v14, s4, v15 bitop3:0xde
	s_lshl_b32 s4, s6, 12
	v_bitop3_b32 v12, v12, v15, v13 bitop3:0x36
	s_and_b32 s4, s4, 0x3000
	v_or_b32_e32 v137, s4, v12
	v_lshl_add_u64 v[12:13], v[8:9], 0, s[46:47]
	s_add_i32 m0, s31, 0x18000
	s_nop 0
	global_load_lds_dwordx4 v[12:13], off
	v_lshl_add_u64 v[12:13], v[8:9], 0, s[18:19]
	s_add_i32 m0, s31, 0x1a000
	s_add_i32 s36, s31, 0x8000
	global_load_lds_dwordx4 v[12:13], off
	v_lshl_add_u64 v[12:13], v[10:11], 0, s[46:47]
	s_mov_b32 m0, s36
	s_add_i32 s37, s31, 0xa000
	global_load_lds_dwordx4 v[12:13], off
	v_lshl_add_u64 v[10:11], v[10:11], 0, s[18:19]
	s_mov_b32 m0, s37
	s_mov_b64 s[4:5], 0x10080
	global_load_lds_dwordx4 v[10:11], off
	v_lshl_add_u64 v[10:11], v[8:9], 0, s[4:5]
	s_add_i32 m0, s31, 0x1c000
	v_lshl_add_u64 v[8:9], v[8:9], 0, s[68:69]
	global_load_lds_dwordx4 v[10:11], off
	s_add_i32 m0, s31, 0x1e000
	v_readlane_b32 s4, v231, 1
	global_load_lds_dwordx4 v[8:9], off
	s_waitcnt vmcnt(10)
	s_barrier
	v_readlane_b32 s5, v231, 2
	s_add_u32 s2, s2, s4
	s_waitcnt vmcnt(6)
	s_addc_u32 s3, s3, s5
	s_add_u32 s38, s2, 0x1be00000
	s_mov_b32 s42, 0
	s_addc_u32 s39, s3, 0
	v_add_u32_e32 v138, 0, v14
	s_mov_b32 s40, 0
	s_mov_b64 s[6:7], s[10:11]
	s_mov_b64 s[8:9], s[12:13]
	s_mov_b32 s41, s42
	s_barrier

; #define G_STAGE(bufoff, gbase, o0, h64) do { \
;         __builtin_amdgcn_global_load_lds((const unsigned*)((const char*)(gbase) + (o0)), (LAS unsigned*)(lds + (bufoff) + ldsw), 16, 0, 0); \
;         __builtin_amdgcn_global_load_lds((const unsigned*)((const char*)(gbase) + (h64) + (o0)), (LAS unsigned*)(lds + (bufoff) + ldsw + 8192), 16, 0, 0); } while (0)
; #define G_WAIT_V(n) asm volatile("s_waitcnt vmcnt(" #n ")" ::: "memory")
; #define G_BAR __builtin_amdgcn_s_barrier()
;     ...
;     const unsigned Rb0 = (unsigned)((R0 & ~31) + perm32(R0 & 31)), c1 = (unsigned)(C0 >> 4), c0b = (unsigned)((C0 & 15) * 2);
;     const unsigned ldsw = (unsigned)wid * 1024u;
;     const int aoff = lds_byte(wr * 64 + fr, fq * 8), boff = lds_byte(wc * 32 + fr, fq * 8);
;     constexpr Shape cs = shape_of<PH, SUB>(); constexpr bool FP8 = (PH == PH_MERGE && (SUB & 1) == 0);
;     const unsigned cA0 = (unsigned)R0 * cs.rsA + c1 * cs.ssA + c0b, cB0 = (Rb0 * cs.Kb + (unsigned)C0) * 2u;
;     ...
;     G_STAGE(G_SB(0, 0), cB, cB0, qB); G_STAGE(G_SA(0, 0), cA, cA0, qA); G_STAGE(G_SB(0, 1), cB + chB, cB0, qB); G_STAGE(G_SA(0, 1), cA + chA, cA0, qA);
;     if (wr == 1) G_BAR;
;     G_WAIT_V(4); G_BAR;
;     G_STAGE(G_SB(1, 0), cB + kB, cB0, qB); G_STAGE(G_SA(1, 0), cA + ckA, cA0, qA); G_STAGE(G_SB(1, 1), cB + chB + kB, cB0, qB);
;     G_WAIT_V(6); G_BAR;
.LBB0_1276:
	v_and_b32_e32 v15, 15, v180
	v_and_b32_e32 v16, 48, v180
	v_lshlrev_b32_e32 v15, 6, v15
	v_lshlrev_b32_e32 v18, 2, v180
	v_or_b32_e32 v17, v15, v16
	s_lshl_b32 s4, s9, 13
	v_and_b32_e32 v18, 32, v18
	v_bitop3_b32 v15, v15, v18, v16 bitop3:0x36
	v_bitop3_b32 v18, v17, s4, v18 bitop3:0xde
	s_lshl_b32 s4, s8, 12
	s_and_b32 s4, s4, 0x3000
	v_or_b32_e32 v181, s4, v15
	v_lshl_add_u64 v[16:17], v[8:9], 0, s[46:47]
	s_add_i32 m0, s29, 0x18000
	s_mov_b64 s[4:5], 0x20080
	s_nop 0
	global_load_lds_dwordx4 v[16:17], off
	v_lshl_add_u64 v[16:17], v[8:9], 0, s[4:5]
	s_add_i32 m0, s29, 0x1a000
	s_add_i32 s35, s29, 0x8000
	global_load_lds_dwordx4 v[16:17], off
	v_lshl_add_u64 v[16:17], v[10:11], 0, s[46:47]
	s_mov_b32 m0, s35
	s_add_i32 s36, s29, 0xa000
	global_load_lds_dwordx4 v[16:17], off
	v_lshl_add_u64 v[10:11], v[10:11], 0, s[4:5]
	s_mov_b32 m0, s36
	s_mov_b64 s[4:5], 0x40080
	global_load_lds_dwordx4 v[10:11], off
	v_lshl_add_u64 v[10:11], v[8:9], 0, s[4:5]
	s_add_i32 m0, s29, 0x1c000
	s_mov_b64 s[4:5], 0x60080
	global_load_lds_dwordx4 v[10:11], off
	v_lshl_add_u64 v[8:9], v[8:9], 0, s[4:5]
	s_add_i32 m0, s29, 0x1e000
	s_add_u32 s8, s2, 0x17e00000
	global_load_lds_dwordx4 v[8:9], off
	s_waitcnt vmcnt(10)
	s_barrier
	s_addc_u32 s9, s3, 0
	v_readlane_b32 s4, v231, 62
	s_bitcmp1_b32 s4, 0
	s_cselect_b32 s4, 0x2400000, 0
	s_add_u32 s4, s2, s4
	s_addc_u32 s5, s3, 0
	s_add_u32 s37, s4, 0x2180000
	s_addc_u32 s38, s5, 0
	s_add_u32 s10, s2, 0xae00000
	s_addc_u32 s11, s3, 0
	s_add_u32 s12, s2, 0x6800000
	s_addc_u32 s13, s3, 0
	s_add_u32 s39, s2, 0xa800000
	s_addc_u32 s42, s3, 0
	v_readlane_b32 s4, v231, 1
	v_readlane_b32 s5, v231, 2
	s_add_u32 s2, s2, s4
	v_lshlrev_b32_e32 v0, 14, v0
	s_waitcnt vmcnt(6)
	s_addc_u32 s3, s3, s5
	v_and_b32_e32 v0, 0xffff8000, v0
	s_add_u32 s43, s2, 0x1be00000
	v_lshl_add_u32 v0, v12, 11, v0
	s_mov_b32 s33, 0
	s_addc_u32 s50, s3, 0
	v_add3_u32 v158, v0, v14, v13
	v_mov_b32_e32 v159, v1
	v_add_u32_e32 v182, 0, v18
	s_mov_b32 s51, 0
	s_barrier
	s_branch .LBB0_1278
